# baseline (speedup 1.0000x reference)
;     ...
;     f32x4 acc[2][2][4][2];
; #pragma unroll
;     for (int a = 0; a < 2; ++a)
; #pragma unroll
;         for (int b = 0; b < 2; ++b)
; #pragma unroll
;             for (int m = 0; m < 4; ++m)
; #pragma unroll
;                 for (int n = 0; n < 2; ++n) acc[a][b][m][n] = (f32x4){0.f, 0.f, 0.f, 0.f};
.LBB0_1440:
	s_add_u32 s40, s4, 0x100
	s_addc_u32 s41, s5, 0
	s_mov_b32 s42, -2
	s_waitcnt lgkmcnt(0)
	v_mov_b64_e32 v[0:1], 0
	v_mov_b64_e32 v[2:3], 0
	v_mov_b64_e32 v[4:5], 0
	v_mov_b64_e32 v[6:7], 0
	v_mov_b64_e32 v[8:9], 0
	v_mov_b64_e32 v[10:11], 0
	v_mov_b64_e32 v[12:13], 0
	v_mov_b64_e32 v[14:15], 0
	v_mov_b64_e32 v[16:17], 0
	v_mov_b64_e32 v[18:19], 0
	v_mov_b64_e32 v[20:21], 0
	v_mov_b64_e32 v[22:23], 0
	v_mov_b64_e32 v[24:25], 0
	v_mov_b64_e32 v[26:27], 0
	v_mov_b64_e32 v[28:29], 0
	v_mov_b64_e32 v[30:31], 0
	v_mov_b64_e32 v[32:33], 0
	v_mov_b64_e32 v[34:35], 0
	v_mov_b64_e32 v[36:37], 0
	v_mov_b64_e32 v[38:39], 0
	v_mov_b64_e32 v[40:41], 0
	v_mov_b64_e32 v[42:43], 0
	v_mov_b64_e32 v[44:45], 0
	v_mov_b64_e32 v[46:47], 0
	v_mov_b64_e32 v[48:49], 0
	v_mov_b64_e32 v[50:51], 0
	v_mov_b64_e32 v[52:53], 0
	v_mov_b64_e32 v[54:55], 0
	v_mov_b64_e32 v[56:57], 0
	v_mov_b64_e32 v[58:59], 0
	v_mov_b64_e32 v[60:61], 0
	v_mov_b64_e32 v[62:63], 0
	v_mov_b64_e32 v[66:67], 0
	v_mov_b64_e32 v[68:69], 0
	v_mov_b64_e32 v[70:71], 0
	v_mov_b64_e32 v[72:73], 0
	v_mov_b64_e32 v[74:75], 0
	v_mov_b64_e32 v[76:77], 0
	v_mov_b64_e32 v[78:79], 0
	v_mov_b64_e32 v[80:81], 0
	v_mov_b64_e32 v[82:83], 0
	v_mov_b64_e32 v[84:85], 0
	v_mov_b64_e32 v[86:87], 0
	v_mov_b64_e32 v[88:89], 0
	v_mov_b64_e32 v[90:91], 0
	v_mov_b64_e32 v[92:93], 0
	v_mov_b64_e32 v[94:95], 0
	v_mov_b64_e32 v[96:97], 0
	v_mov_b64_e32 v[98:99], 0
	v_mov_b64_e32 v[100:101], 0
	v_mov_b64_e32 v[102:103], 0
	v_mov_b64_e32 v[104:105], 0
	v_mov_b64_e32 v[106:107], 0
	v_mov_b64_e32 v[108:109], 0
	v_mov_b64_e32 v[110:111], 0
	v_mov_b64_e32 v[112:113], 0
	v_mov_b64_e32 v[114:115], 0
	v_mov_b64_e32 v[116:117], 0
	v_mov_b64_e32 v[118:119], 0
	v_mov_b64_e32 v[120:121], 0
	v_mov_b64_e32 v[122:123], 0
	v_mov_b64_e32 v[124:125], 0
	v_mov_b64_e32 v[126:127], 0
	v_mov_b64_e32 v[128:129], 0
